# speedup vs baseline: 1.0165x; 1.0014x over previous
; #define otid() otid_(wid_s_)
; #define SLOAD(k0) do { SLOAD_KR(k0); SLOAD_V(k0); } while (0)
; #define SWRITE(b) do { SWRITE_KR(b); SWRITE_V(b); } while (0)
; #define SWAIT() asm volatile("s_waitcnt vmcnt(0)" ::: "memory")
; DEVI void attn_item(const u16* __restrict__ Qb, const u16* __restrict__ KNh, const u16* __restrict__ VTh, int Lpad, const u16* __restrict__ KRb,
;                     const u16* __restrict__ SZb, u16* __restrict__ AOb, int NT, char* lds, const int wid_s_) {
;   const int tid = otid(), wid = tid >> 6, lane = tid & 63, r32 = lane & 31, hi = lane >> 5;
;   char* V_lds = lds; char* K_lds = lds + 2 * SHM_V; char* R_lds = lds + 2 * SHM_V + 2 * SHM_K;
;   char* Qrs = lds + 2 * SHM_V + 2 * SHM_K + 2 * SHM_R + wid * 4096;
;   float* wsf = (float*)(lds + 2 * SHM_V + 2 * SHM_K + 2 * SHM_R + 32768) + wid * 64; float* li_l = wsf; float* al_l = wsf + 32;
;   float m_reg = -1e30f, l_reg = 0; f32x16 o[4] = {}; bf16x8 qr[8];
;   const u16* Qw = Qb + (size_t)(wid * 32 + r32) * LDQ + hi * 8;
; #pragma unroll
;   for (int d0 = 0; d0 < 8; ++d0) qr[d0] = __builtin_nontemporal_load(reinterpret_cast<const bf16x8*>(Qw + d0 * 16));
; #pragma unroll
;   for (int d0 = 0; d0 < 4; ++d0) *reinterpret_cast<bf16x8*>(Qrs + RSWZ(r32, (d0 * 16 + hi * 8) * 2)) = *reinterpret_cast<const bf16x8*>(Qw + 128 + d0 * 16);
;   const int sr = tid >> 4, sc = (tid & 15) * 8;
;   const int vd = tid >> 3, vc = tid & 7;
;   const int rr_ = tid >> 3, rc_ = (tid & 7) * 8;
;   bf16x8 vs0, vs1, ks0, ks1, rs0;
;   const unsigned vo_k = (unsigned)((sr * LDK + sc) * 2), vo_r = (unsigned)((rr_ * 64 + rc_) * 2), vo_v = (unsigned)((vd * Lpad + vc * 8) * 2);
;   const size_t vhalf = (size_t)64 * Lpad * 2;
;     ...
;   f32x16 pA0, pA1, pB0, pB1; float mnA, mnB, alA, alB; bf16x8 pa0, pa1, pa2, pa3;
;   SLOAD(0); SWAIT(); SWRITE(0); __syncthreads();
.LBB0_980:
	s_lshr_b32 s2, s1, s93
	s_and_b32 s46, s1, s31
	s_lshr_b32 s8, s2, 4
	s_and_b32 s1, s2, 15
	s_mul_i32 s13, s8, s29
	s_lshl_b64 s[6:7], s[46:47], 8
	s_mul_hi_u32 s9, s8, s29
	s_add_u32 s56, s13, s6
	s_addc_u32 s57, s9, s7
	s_mul_i32 s6, s57, 0x1800
	s_mul_hi_u32 s7, s56, 0x1800
	s_add_i32 s7, s7, s6
	s_mul_i32 s6, s56, 0x1800
	s_add_u32 s6, s94, s6
	s_addc_u32 s7, s95, s7
	s_mul_i32 s9, s1, 0x180
	s_add_u32 s14, s6, s9
	s_mul_hi_u32 s17, s8, s28
	s_mul_i32 s16, s8, s28
	s_addc_u32 s15, s7, 0
	s_lshl_b64 s[8:9], s[16:17], 12
	s_add_u32 s6, s52, s8
	v_mov_b32_e32 v51, v207
	s_addc_u32 s7, s53, s9
	s_lshl_b32 s35, s1, 7
	s_lshl_b32 s1, s1, 8
	s_add_u32 s18, s6, s1
	v_ashrrev_i32_e32 v40, 6, v51
	v_and_b32_e32 v176, 31, v51
	v_lshlrev_b32_e32 v175, 5, v40
	s_addc_u32 s19, s7, 0
	s_lshl_b32 s46, s2, 7
	v_bfe_u32 v174, v51, 5, 1
	v_or_b32_e32 v2, v175, v176
	v_mov_b64_e32 v[0:1], s[14:15]
	v_lshlrev_b32_e32 v42, 4, v51
	s_mul_hi_u32 s7, s46, s28
	s_mul_i32 s6, s46, s28
	v_mad_i64_i32 v[0:1], s[14:15], v2, s89, v[0:1]
	v_lshlrev_b32_e32 v160, 4, v174
	v_mov_b32_e32 v161, v205
	v_ashrrev_i32_e32 v41, 4, v51
	v_and_b32_e32 v49, 0xf0, v42
	v_ashrrev_i32_e32 v16, 3, v51
	s_lshl_b64 s[6:7], s[6:7], 1
	v_lshl_add_u64 v[38:39], v[0:1], 0, v[160:161]
	v_lshl_or_b32 v204, v41, 12, v49
	v_lshlrev_b32_e32 v43, 7, v16
	v_and_b32_e32 v17, 0x70, v42
	v_mul_lo_u32 v16, s5, v16
	s_add_u32 s6, s70, s6
	global_load_dwordx4 v[0:3], v[38:39], off offset:256
	global_load_dwordx4 v[4:7], v[38:39], off offset:288
	global_load_dwordx4 v[8:11], v[38:39], off offset:320
	global_load_dwordx4 v[12:15], v[38:39], off offset:352
	v_or_b32_e32 v48, v43, v17
	v_or_b32_e32 v50, v17, v16
	v_lshl_add_u64 v[16:17], s[18:19], 0, v[204:205]
	s_mov_b32 s2, 0x20000
	s_addc_u32 s7, s71, s7
	s_lshl_b64 s[58:59], s[16:17], 7
	v_add_co_u32_e32 v22, vcc, s2, v16
	s_add_u32 s16, s44, s58
	s_nop 0
	v_addc_co_u32_e32 v23, vcc, 0, v17, vcc
	s_addc_u32 s17, s45, s59
	global_load_dwordx4 v[18:21], v204, s[18:19]
	s_nop 0
	global_load_dwordx4 v[22:25], v[22:23], off
	s_nop 0
	global_load_dwordx4 v[26:29], v48, s[16:17]
	s_add_u32 s14, s6, s54
	s_addc_u32 s15, s7, 0
	global_load_dwordx4 v[30:33], v50, s[6:7]
	global_load_dwordx4 v[34:37], v50, s[14:15]
	global_load_dwordx4 v[96:99], v[38:39], off nt
	global_load_dwordx4 v[100:103], v[38:39], off offset:32 nt
	global_load_dwordx4 v[104:107], v[38:39], off offset:64 nt
	global_load_dwordx4 v[108:111], v[38:39], off offset:96 nt
	global_load_dwordx4 v[112:115], v[38:39], off offset:128 nt
	global_load_dwordx4 v[116:119], v[38:39], off offset:160 nt
	global_load_dwordx4 v[120:123], v[38:39], off offset:192 nt
	global_load_dwordx4 v[124:127], v[38:39], off offset:224 nt
	v_mov_b32_e32 v45, 0x14000
	v_lshlrev_b32_e32 v44, 3, v51
	v_lshl_add_u32 v183, v40, 12, v45
	v_lshlrev_b32_e32 v72, 7, v176
	v_and_b32_e32 v73, 0x70, v44
	v_or_b32_e32 v40, v183, v72
	v_bitop3_b32 v44, v160, v44, s90 bitop3:0x78
	v_bitop3_b32 v45, v160, v73, 32 bitop3:0x36
	v_bitop3_b32 v46, v160, v73, 64 bitop3:0x36
	v_or_b32_e32 v44, v40, v44
	v_or_b32_e32 v45, v40, v45
	s_movk_i32 s2, 0x60
	v_or_b32_e32 v74, 64, v160
	v_or_b32_e32 v75, 0x60, v160
	v_bitop3_b32 v177, v160, v72, v73 bitop3:0xde
	v_or_b32_e32 v195, 0x10000, v177
	v_or_b32_e32 v196, 0x11000, v177
	v_bitop3_b32 v180, v74, v72, v73 bitop3:0xde
	v_or_b32_e32 v199, 0x10000, v180
	v_or_b32_e32 v200, 0x11000, v180
	s_waitcnt vmcnt(16)
	ds_write_b128 v44, v[0:3]
	s_waitcnt vmcnt(15)
	ds_write_b128 v45, v[4:7]
	v_or_b32_e32 v0, v40, v46
	s_waitcnt vmcnt(14)
	ds_write_b128 v0, v[8:11]
	v_bitop3_b32 v0, v160, v73, s2 bitop3:0x36
	v_or_b32_e32 v0, v40, v0
	v_xor_b32_e32 v1, v42, v51
	s_waitcnt vmcnt(13)
	ds_write_b128 v0, v[12:15]
	v_lshlrev_b32_e32 v0, 8, v41
	s_movk_i32 s2, 0xf0
	v_and_or_b32 v185, v1, s90, v43
	v_and_or_b32 v184, v1, s2, v0
	v_add_u32_e32 v186, 0x10000, v185
	s_waitcnt vmcnt(0)
	s_waitcnt vmcnt(12)
	ds_write_b128 v184, v[18:21] offset:32768
	s_waitcnt vmcnt(11)
	ds_write_b128 v184, v[22:25] offset:40960
	s_waitcnt vmcnt(10)
	ds_write_b128 v186, v[26:29]
	s_waitcnt vmcnt(9)
	ds_write_b128 v185, v[30:33]
	s_waitcnt vmcnt(8)
	ds_write_b128 v185, v[34:37] offset:8192
	v_lshlrev_b32_e32 v26, 8, v176
	v_bitop3_b32 v187, v160, v26, v49 bitop3:0xde
	s_waitcnt lgkmcnt(0)
	s_barrier
; #define SLOAD(k0) do { SLOAD_KR(k0); SLOAD_V(k0); } while (0)
; #define SWRITE(b) do { SWRITE_KR(b); SWRITE_V(b); } while (0)
; #define SWAIT() asm volatile("s_waitcnt vmcnt(0)" ::: "memory")
; DEVI void qkt(f32x16& p0, f32x16& p1, const char* Ks, const char* Rs, const bf16x8* qr, const char* Qrs, int r32, int hi) {
;   p0 = f32x16{}; p1 = f32x16{};
; #pragma unroll
;   for (int d0 = 0; d0 < 8; ++d0) { int cb = (d0 * 16 + hi * 8) * 2;
;     bf16x8 b0 = *reinterpret_cast<const bf16x8*>(Ks + KSWZ(r32, cb));
;     bf16x8 b1 = *reinterpret_cast<const bf16x8*>(Ks + KSWZ(32 + r32, cb));
;     p0 = __builtin_amdgcn_mfma_f32_32x32x16_bf16(b0, qr[d0], p0, 0, 0, 0);
;     p1 = __builtin_amdgcn_mfma_f32_32x32x16_bf16(b1, qr[d0], p1, 0, 0, 0); }
; #pragma unroll
;   for (int d0 = 0; d0 < 4; ++d0) { int cb = (d0 * 16 + hi * 8) * 2;
;     bf16x8 b0 = *reinterpret_cast<const bf16x8*>(Rs + RSWZ(r32, cb));
;     bf16x8 b1 = *reinterpret_cast<const bf16x8*>(Rs + RSWZ(32 + r32, cb));
;     bf16x8 qf = *reinterpret_cast<const bf16x8*>(Qrs + RSWZ(r32, cb));
;     p0 = __builtin_amdgcn_mfma_f32_32x32x16_bf16(b0, qf, p0, 0, 0, 0);
;     p1 = __builtin_amdgcn_mfma_f32_32x32x16_bf16(b1, qf, p1, 0, 0, 0); }
; }
; DEVI void attn_item(const u16* __restrict__ Qb, const u16* __restrict__ KNh, const u16* __restrict__ VTh, int Lpad, const u16* __restrict__ KRb,
;                     const u16* __restrict__ SZb, u16* __restrict__ AOb, int NT, char* lds, const int wid_s_) {
;     ...
;   SLOAD(0); SWAIT(); SWRITE(0); __syncthreads();
;   qkt(pA0, pA1, K_lds, R_lds, qr, Qrs, r32, hi); partialSM(pA0, pA1, m_reg, mnA, alA);
;   SLOAD(64);
;   SWAIT(); SWRITE(1); __syncthreads();
	ds_read_b128 v[0:3], v187 offset:32768
	ds_read_b128 v[18:21], v187 offset:40960
	s_waitcnt vmcnt(7) lgkmcnt(1)
	v_mfma_f32_32x32x16_bf16 v[0:15], v[0:3], v[96:99], 0
	v_or_b32_e32 v27, 32, v160
	v_bitop3_b32 v188, v27, v26, v49 bitop3:0xde
	v_bitop3_b32 v189, v74, v26, v49 bitop3:0xde
	v_bitop3_b32 v190, v75, v26, v49 bitop3:0xde
	v_bitop3_b32 v161, v27, v72, v73 bitop3:0xde
	v_or_b32_e32 v197, 0x10000, v161
	s_mov_b32 s2, 0x40000
	s_waitcnt lgkmcnt(0)
	v_mfma_f32_32x32x16_bf16 v[32:47], v[18:21], v[96:99], 0
	ds_read_b128 v[18:21], v188 offset:32768
	ds_read_b128 v[22:25], v188 offset:40960
	v_or_b32_e32 v198, 0x11000, v161
	v_bitop3_b32 v179, v75, v72, v73 bitop3:0xde
	v_or_b32_e32 v201, 0x10000, v179
	v_or_b32_e32 v202, 0x11000, v179
	v_add_u32_e32 v203, 0x12000, v185
	s_mov_b32 s26, s12
	s_waitcnt vmcnt(6) lgkmcnt(1)
	v_mfma_f32_32x32x16_bf16 v[0:15], v[18:21], v[100:103], v[0:15]
	s_mov_b32 s27, s12
	s_mov_b32 s13, s12
	s_mov_b32 s18, s12
	s_mov_b32 s19, s12
	s_mov_b32 s20, s12
	s_mov_b32 s21, s12
	s_mov_b32 s22, s12
	s_waitcnt lgkmcnt(0)
	v_mfma_f32_32x32x16_bf16 v[32:47], v[22:25], v[100:103], v[32:47]
	ds_read_b128 v[18:21], v189 offset:32768
	ds_read_b128 v[22:25], v189 offset:40960
	s_mov_b32 s23, s12
	s_mov_b32 s24, s12
	s_mov_b32 s25, s12
	v_mov_b32_e32 v182, 0
	s_waitcnt vmcnt(5) lgkmcnt(1)
	v_mfma_f32_32x32x16_bf16 v[0:15], v[18:21], v[104:107], v[0:15]
	s_waitcnt lgkmcnt(0)
	v_mfma_f32_32x32x16_bf16 v[32:47], v[22:25], v[104:107], v[32:47]
	ds_read_b128 v[18:21], v190 offset:32768
	ds_read_b128 v[22:25], v190 offset:40960
	s_waitcnt vmcnt(4) lgkmcnt(1)
	v_mfma_f32_32x32x16_bf16 v[0:15], v[18:21], v[108:111], v[0:15]
	v_or_b32_e32 v18, 0x80, v160
	v_bitop3_b32 v191, v18, v26, v49 bitop3:0xde
	s_waitcnt lgkmcnt(0)
	v_mfma_f32_32x32x16_bf16 v[32:47], v[22:25], v[108:111], v[32:47]
	ds_read_b128 v[18:21], v191 offset:32768
	ds_read_b128 v[22:25], v191 offset:40960
	s_waitcnt vmcnt(3) lgkmcnt(1)
	v_mfma_f32_32x32x16_bf16 v[0:15], v[18:21], v[112:115], v[0:15]
	v_or_b32_e32 v18, 0xa0, v160
	v_bitop3_b32 v192, v18, v26, v49 bitop3:0xde
	s_waitcnt lgkmcnt(0)
	v_mfma_f32_32x32x16_bf16 v[32:47], v[22:25], v[112:115], v[32:47]
	ds_read_b128 v[18:21], v192 offset:32768
	ds_read_b128 v[22:25], v192 offset:40960
	s_waitcnt vmcnt(2) lgkmcnt(1)
	v_mfma_f32_32x32x16_bf16 v[0:15], v[18:21], v[116:119], v[0:15]
	v_or_b32_e32 v18, 0xc0, v160
	v_bitop3_b32 v193, v18, v26, v49 bitop3:0xde
	s_waitcnt lgkmcnt(0)
	v_mfma_f32_32x32x16_bf16 v[32:47], v[22:25], v[116:119], v[32:47]
	ds_read_b128 v[18:21], v193 offset:32768
	ds_read_b128 v[22:25], v193 offset:40960
	s_waitcnt vmcnt(1) lgkmcnt(1)
	v_mfma_f32_32x32x16_bf16 v[0:15], v[18:21], v[120:123], v[0:15]
	v_or_b32_e32 v18, 0xe0, v160
	v_bitop3_b32 v194, v18, v26, v49 bitop3:0xde
	v_mov_b32_e32 v49, v205
	v_lshl_add_u64 v[30:31], s[16:17], 0, v[48:49]
	s_mov_b32 s16, s12
	s_mov_b32 s17, s12
	v_lshl_add_u64 v[166:167], s[58:59], 0, v[48:49]
	v_add_u32_e32 v166, 0xa0e5000, v166
	s_waitcnt lgkmcnt(0)
	v_mfma_f32_32x32x16_bf16 v[32:47], v[22:25], v[120:123], v[32:47]
	ds_read_b128 v[18:21], v194 offset:32768
	ds_read_b128 v[22:25], v194 offset:40960
	s_waitcnt vmcnt(0) lgkmcnt(1)
	v_mfma_f32_32x32x16_bf16 v[0:15], v[18:21], v[124:127], v[0:15]
	ds_read_b128 v[18:21], v195
	s_waitcnt lgkmcnt(1)
	v_mfma_f32_32x32x16_bf16 v[32:47], v[22:25], v[124:127], v[32:47]
	v_or_b32_e32 v22, v183, v177
	ds_read_b128 v[22:25], v22
	ds_read_b128 v[26:29], v196
	ds_read_b128 v[52:55], v197
	s_waitcnt lgkmcnt(2)
	v_mfma_f32_32x32x16_bf16 v[0:15], v[18:21], v[22:25], v[0:15]
	v_or_b32_e32 v18, v183, v161
	ds_read_b128 v[18:21], v18
	s_waitcnt lgkmcnt(2)
	v_mfma_f32_32x32x16_bf16 v[32:47], v[26:29], v[22:25], v[32:47]
	v_add_co_u32_e32 v22, vcc, s2, v16
	s_mov_b32 s2, 0x60000
	s_nop 0
	v_addc_co_u32_e32 v23, vcc, 0, v17, vcc
	v_add_co_u32_e32 v16, vcc, s2, v16
	s_movk_i32 s2, 0x2000
	s_nop 0
	v_addc_co_u32_e32 v17, vcc, 0, v17, vcc
	global_load_dwordx4 v[56:59], v[22:23], off
	global_load_dwordx4 v[60:63], v[16:17], off
	v_add_co_u32_e32 v16, vcc, s2, v30
	s_waitcnt lgkmcnt(0)
	v_mfma_f32_32x32x16_bf16 v[0:15], v[52:55], v[18:21], v[0:15]
	v_addc_co_u32_e32 v17, vcc, 0, v31, vcc
	global_load_dwordx4 v[64:67], v[16:17], off
	global_load_dwordx4 v[68:71], v50, s[6:7] offset:128
	global_load_dwordx4 v[52:55], v50, s[14:15] offset:128
	ds_read_b128 v[22:25], v198
	ds_read_b128 v[26:29], v199
	v_or_b32_e32 v16, v183, v180
	s_waitcnt lgkmcnt(1)
	v_mfma_f32_32x32x16_bf16 v[32:47], v[22:25], v[18:21], v[32:47]
	ds_read_b128 v[16:19], v16
	ds_read_b128 v[20:23], v200
	ds_read_b128 v[72:75], v201
	v_and_b32_e32 v30, 0x3fffffc0, v51
	v_mov_b32_e32 v24, 0x1c000
	v_lshl_add_u32 v178, v30, 2, v24
	v_mov_b32_e32 v51, v205
	s_mov_b32 s14, s12
	s_waitcnt lgkmcnt(2)
	v_mfma_f32_32x32x16_bf16 v[0:15], v[26:29], v[16:19], v[0:15]
	s_mov_b32 s15, s12
	s_mov_b32 s2, 4
	v_cmp_eq_u32_e64 s[6:7], 0, v174
	v_lshl_or_b32 v181, v176, 2, v178
	s_waitcnt lgkmcnt(1)
	v_mfma_f32_32x32x16_bf16 v[32:47], v[20:23], v[16:19], v[32:47]
	v_or_b32_e32 v16, v183, v179
	ds_read_b128 v[76:79], v202
	ds_read_b128 v[80:83], v16
	s_waitcnt vmcnt(0)
	s_waitcnt vmcnt(4)
	ds_write_b128 v184, v[56:59] offset:49152
	s_waitcnt vmcnt(3)
	ds_write_b128 v184, v[60:63] offset:57344
	s_waitcnt lgkmcnt(2)
	v_mfma_f32_32x32x16_bf16 v[0:15], v[72:75], v[80:83], v[0:15]
	s_waitcnt vmcnt(2)
	ds_write_b128 v203, v[64:67]
	s_waitcnt vmcnt(1)
	ds_write_b128 v185, v[68:71] offset:16384
	s_waitcnt vmcnt(0)
; #define SLOAD(k0) do { SLOAD_KR(k0); SLOAD_V(k0); } while (0)
; DEVI void partialSM(f32x16& p0, f32x16& p1, float& m_reg, float& mn, float& alpha) {
;   constexpr float C = ASCALE * 1.4426950408889634f;
;   float pmax = p0[0];
; #pragma unroll
;   for (int r = 1; r < 16; ++r) pmax = fmaxf(pmax, p0[r]);
; #pragma unroll
;   for (int r = 0; r < 16; ++r) pmax = fmaxf(pmax, p1[r]);
;   { auto rr = __builtin_amdgcn_permlane32_swap(__float_as_uint(pmax), __float_as_uint(pmax), false, false);
;     pmax = fmaxf(__uint_as_float(rr[0]), __uint_as_float(rr[1])); }
;   if (__builtin_expect(__all(pmax - m_reg <= ATHR / ASCALE), 1)) { mn = m_reg; alpha = 1.f; }
;   else { mn = fmaxf(m_reg, pmax); alpha = __builtin_amdgcn_exp2f((m_reg - mn) * C); m_reg = mn; }
;   float mnC = -mn * C;
; #pragma unroll
;   for (int r = 0; r < 16; ++r) p0[r] = fmaf(p0[r], C, mnC);
; #pragma unroll
;   for (int r = 0; r < 16; ++r) p1[r] = fmaf(p1[r], C, mnC);
; #pragma unroll
;   for (int r = 0; r < 16; ++r) p0[r] = __builtin_amdgcn_exp2f(p0[r]);
; }
; DEVI void attn_item(const u16* __restrict__ Qb, const u16* __restrict__ KNh, const u16* __restrict__ VTh, int Lpad, const u16* __restrict__ KRb,
;                     const u16* __restrict__ SZb, u16* __restrict__ AOb, int NT, char* lds, const int wid_s_) {
;     ...
;   float m_reg = -1e30f, l_reg = 0; f32x16 o[4] = {}; bf16x8 qr[8];
;   const u16* Qw = Qb + (size_t)(wid * 32 + r32) * LDQ + hi * 8;
; #pragma unroll
;   for (int d0 = 0; d0 < 8; ++d0) qr[d0] = __builtin_nontemporal_load(reinterpret_cast<const bf16x8*>(Qw + d0 * 16));
; #pragma unroll
;   for (int d0 = 0; d0 < 4; ++d0) *reinterpret_cast<bf16x8*>(Qrs + RSWZ(r32, (d0 * 16 + hi * 8) * 2)) = *reinterpret_cast<const bf16x8*>(Qw + 128 + d0 * 16);
;   const int sr = tid >> 4, sc = (tid & 15) * 8;
;   const int vd = tid >> 3, vc = tid & 7;
;   const int rr_ = tid >> 3, rc_ = (tid & 7) * 8;
;   bf16x8 vs0, vs1, ks0, ks1, rs0;
;   const unsigned vo_k = (unsigned)((sr * LDK + sc) * 2), vo_r = (unsigned)((rr_ * 64 + rc_) * 2), vo_v = (unsigned)((vd * Lpad + vc * 8) * 2);
;   const size_t vhalf = (size_t)64 * Lpad * 2;
;     ...
;   f32x16 pA0, pA1, pB0, pB1; float mnA, mnB, alA, alB; bf16x8 pa0, pa1, pa2, pa3;
;   SLOAD(0); SWAIT(); SWRITE(0); __syncthreads();
;   qkt(pA0, pA1, K_lds, R_lds, qr, Qrs, r32, hi); partialSM(pA0, pA1, m_reg, mnA, alA);
	ds_write_b128 v185, v[52:55] offset:24576
	v_mov_b64_e32 v[30:31], s[26:27]
	v_mov_b64_e32 v[28:29], s[24:25]
	s_nop 3
	v_max_f32_e32 v72, v1, v1
	v_max_f32_e32 v73, v0, v0
	v_mfma_f32_32x32x16_bf16 v[32:47], v[76:79], v[80:83], v[32:47]
	v_max_f32_e32 v72, v73, v72
	v_max3_f32 v72, v72, v2, v3
	v_max3_f32 v72, v72, v4, v5
	v_max3_f32 v72, v72, v6, v7
	v_max3_f32 v72, v72, v8, v9
	v_max3_f32 v72, v72, v10, v11
	v_max3_f32 v72, v72, v12, v13
	v_max3_f32 v72, v72, v14, v15
	s_nop 3
	v_max3_f32 v72, v72, v32, v33
	v_max3_f32 v72, v72, v34, v35
	v_max3_f32 v72, v72, v36, v37
	v_max3_f32 v72, v72, v38, v39
	v_max3_f32 v72, v72, v40, v41
	v_max3_f32 v72, v72, v42, v43
	v_max3_f32 v72, v72, v44, v45
	v_max3_f32 v72, v72, v46, v47
	v_mov_b32_e32 v73, v72
	s_nop 1
	v_permlane32_swap_b32_e32 v72, v73
	v_max_f32_e32 v73, v73, v73
	v_max_f32_e32 v72, v72, v72
	v_max_f32_e32 v72, v72, v73
	v_add_f32_e32 v73, 0x7149f2ca, v72
	v_cmp_ge_f32_e32 vcc, s91, v73
	s_cmp_eq_u64 vcc, exec
	v_max_f32_e32 v53, 0xf149f2ca, v72
	s_cselect_b64 vcc, -1, 0
	v_cndmask_b32_e32 v222, v53, v208, vcc
	v_mul_f32_e32 v52, 0xbdd53b94, v222
	v_fmamk_f32 v0, v0, 0x3dd53b94, v52
	v_exp_f32_e32 v231, v0
	v_fmamk_f32 v0, v1, 0x3dd53b94, v52
	v_exp_f32_e32 v235, v0
	v_fmamk_f32 v0, v2, 0x3dd53b94, v52
	v_exp_f32_e32 v230, v0
	v_fmamk_f32 v0, v3, 0x3dd53b94, v52
	v_exp_f32_e32 v232, v0
	v_fmamk_f32 v0, v4, 0x3dd53b94, v52
	v_exp_f32_e32 v233, v0
	v_fmamk_f32 v0, v5, 0x3dd53b94, v52
	v_exp_f32_e32 v236, v0
	v_fmamk_f32 v0, v6, 0x3dd53b94, v52
	v_exp_f32_e32 v234, v0
	v_fmamk_f32 v0, v7, 0x3dd53b94, v52
	v_exp_f32_e32 v237, v0
	v_fmamk_f32 v0, v8, 0x3dd53b94, v52
	v_exp_f32_e32 v156, v0
	v_fmamk_f32 v0, v9, 0x3dd53b94, v52
	v_exp_f32_e32 v157, v0
	v_fmamk_f32 v0, v10, 0x3dd53b94, v52
	v_exp_f32_e32 v158, v0
	v_fmamk_f32 v0, v11, 0x3dd53b94, v52
	v_exp_f32_e32 v159, v0
	v_fmamk_f32 v0, v12, 0x3dd53b94, v52
	v_exp_f32_e32 v228, v0
	v_fmamk_f32 v0, v13, 0x3dd53b94, v52
	v_exp_f32_e32 v229, v0
	v_fmamk_f32 v0, v14, 0x3dd53b94, v52
	v_sub_f32_e32 v1, 0xf149f2ca, v53
	v_mul_f32_e32 v1, 0x3dd53b94, v1
	v_exp_f32_e32 v154, v0
	v_mov_b32_e32 v0, s46
	v_mov_b64_e32 v[26:27], s[22:23]
	v_mov_b64_e32 v[24:25], s[20:21]
	v_mov_b64_e32 v[22:23], s[18:19]
	v_mov_b64_e32 v[20:21], s[16:17]
	v_mov_b64_e32 v[18:19], s[14:15]
	v_mov_b64_e32 v[16:17], s[12:13]
	v_exp_f32_e32 v1, v1
	v_mad_u64_u32 v[162:163], s[14:15], s64, v0, v[50:51]
	v_add_u32_e32 v162, s75, v162
	v_pk_fma_f32 v[144:145], v[46:47], s[80:81], v[52:53] op_sel_hi:[1,0,0]
	v_pk_fma_f32 v[140:141], v[44:45], s[80:81], v[52:53] op_sel_hi:[1,0,0]
	v_pk_fma_f32 v[146:147], v[42:43], s[80:81], v[52:53] op_sel_hi:[1,0,0]
	v_pk_fma_f32 v[142:143], v[40:41], s[80:81], v[52:53] op_sel_hi:[1,0,0]
	v_pk_fma_f32 v[148:149], v[38:39], s[80:81], v[52:53] op_sel_hi:[1,0,0]
	v_pk_fma_f32 v[150:151], v[36:37], s[80:81], v[52:53] op_sel_hi:[1,0,0]
	v_pk_fma_f32 v[152:153], v[34:35], s[80:81], v[52:53] op_sel_hi:[1,0,0]
	v_pk_fma_f32 v[80:81], v[32:33], s[80:81], v[52:53] op_sel_hi:[1,0,0]
	v_fmac_f32_e32 v52, 0x3dd53b94, v15
	s_lshl_b64 s[14:15], s[46:47], 1
	v_exp_f32_e32 v155, v52
	s_or_b32 s13, s14, 0x80
	v_mov_b32_e32 v0, s13
	v_cndmask_b32_e64 v220, v1, 1.0, vcc
	v_mad_u64_u32 v[164:165], s[16:17], s28, v0, v[50:51]
	s_mul_i32 s13, s28, s15
	s_or_b32 s8, s8, s1
	v_mov_b64_e32 v[62:63], v[30:31]
	v_mov_b64_e32 v[46:47], v[30:31]
	v_mov_b64_e32 v[0:1], v[16:17]
	v_add_u32_e32 v165, s13, v165
	v_add_u32_e32 v164, s75, v164
	v_lshl_add_u64 v[168:169], s[8:9], 0, v[204:205]
	v_add_u32_e32 v168, 0x22681000, v168
	v_mov_b64_e32 v[60:61], v[28:29]
	v_mov_b64_e32 v[58:59], v[26:27]
	v_mov_b64_e32 v[56:57], v[24:25]
	v_mov_b64_e32 v[54:55], v[22:23]
	v_mov_b64_e32 v[52:53], v[20:21]
	v_mov_b64_e32 v[50:51], v[18:19]
	v_mov_b64_e32 v[48:49], v[16:17]
	v_mov_b64_e32 v[44:45], v[28:29]
	v_mov_b64_e32 v[42:43], v[26:27]
	v_mov_b64_e32 v[40:41], v[24:25]
	v_mov_b64_e32 v[38:39], v[22:23]
	v_mov_b64_e32 v[36:37], v[20:21]
	v_mov_b64_e32 v[34:35], v[18:19]
	v_mov_b64_e32 v[32:33], v[16:17]
	v_mov_b64_e32 v[2:3], v[18:19]
	v_mov_b64_e32 v[4:5], v[20:21]
	v_mov_b64_e32 v[6:7], v[22:23]
	v_mov_b64_e32 v[8:9], v[24:25]
	v_mov_b64_e32 v[10:11], v[26:27]
	v_mov_b64_e32 v[12:13], v[28:29]
	v_mov_b64_e32 v[14:15], v[30:31]
	s_waitcnt lgkmcnt(0)
	v_add_u32_e32 v196, v183, v177
	v_add_u32_e32 v198, v183, v161
	v_add_u32_e32 v200, v183, v180
	v_add_u32_e32 v202, v183, v179
	s_barrier
; #define SBAR() __builtin_amdgcn_sched_barrier(0)
; DEVI void finishSM(f32x16& p0, f32x16& p1, float alpha, float& l_reg, bf16x8& pa0, bf16x8& pa1, bf16x8& pa2, bf16x8& pa3) {
; #pragma unroll
;   for (int r = 0; r < 16; ++r) p1[r] = __builtin_amdgcn_exp2f(p1[r]);
;   float ps = 0;
; #pragma unroll
;   for (int r = 0; r < 16; ++r) ps += p0[r];
; #pragma unroll
;   for (int r = 0; r < 16; ++r) ps += p1[r];
;   { auto rr = __builtin_amdgcn_permlane32_swap(__float_as_uint(ps), __float_as_uint(ps), false, false);
;     ps = __uint_as_float(rr[0]) + __uint_as_float(rr[1]); }
;   l_reg = l_reg * alpha + ps;
;     ...
;   PK4(p0, 0, pa0); PK4(p0, 8, pa1); PK4(p1, 0, pa2); PK4(p1, 8, pa3);
;     ...
; }
; DEVI void mask_tile(f32x16& p0, f32x16& p1, bool nv16) {
; #pragma unroll
;   for (int r = 0; r < 16; ++r) { if (!(nv16 && r < 8)) p0[r] = -1e30f; p1[r] = -1e30f; }
; }
; DEVI void qkt(f32x16& p0, f32x16& p1, const char* Ks, const char* Rs, const bf16x8* qr, const char* Qrs, int r32, int hi) {
;   p0 = f32x16{}; p1 = f32x16{};
; #pragma unroll
;   for (int d0 = 0; d0 < 8; ++d0) { int cb = (d0 * 16 + hi * 8) * 2;
;     bf16x8 b0 = *reinterpret_cast<const bf16x8*>(Ks + KSWZ(r32, cb));
;     bf16x8 b1 = *reinterpret_cast<const bf16x8*>(Ks + KSWZ(32 + r32, cb));
;     p0 = __builtin_amdgcn_mfma_f32_32x32x16_bf16(b0, qr[d0], p0, 0, 0, 0);
;     p1 = __builtin_amdgcn_mfma_f32_32x32x16_bf16(b1, qr[d0], p1, 0, 0, 0); }
; #pragma unroll
;   for (int d0 = 0; d0 < 4; ++d0) { int cb = (d0 * 16 + hi * 8) * 2;
;     bf16x8 b0 = *reinterpret_cast<const bf16x8*>(Rs + RSWZ(r32, cb));
;     bf16x8 b1 = *reinterpret_cast<const bf16x8*>(Rs + RSWZ(32 + r32, cb));
;     bf16x8 qf = *reinterpret_cast<const bf16x8*>(Qrs + RSWZ(r32, cb));
;     p0 = __builtin_amdgcn_mfma_f32_32x32x16_bf16(b0, qf, p0, 0, 0, 0);
;     p1 = __builtin_amdgcn_mfma_f32_32x32x16_bf16(b1, qf, p1, 0, 0, 0); }
; }
; DEVI void attn_item(const u16* __restrict__ Qb, const u16* __restrict__ KNh, const u16* __restrict__ VTh, int Lpad, const u16* __restrict__ KRb,
;                     const u16* __restrict__ SZb, u16* __restrict__ AOb, int NT, char* lds, const int wid_s_) {
;     ...
;   for (int j = 1; j + 1 < NT; j += 2) {
;     SLOAD_KR((j + 1) * 64);
;     SBAR(); qkt(pB0, pB1, K_lds + SHM_K, R_lds + SHM_R, qr, Qrs, r32, hi);
;     finishSM(pA0, pA1, alA, l_reg, pa0, pa1, pa2, pa3); SGB_QK(); SBAR();
.LBB0_981:
	global_load_dwordx4 v[128:131], v168, s[36:37] offset:3072
	v_add_u32_e32 v64, 0x20000, v168
	global_load_dwordx4 v[132:135], v64, s[36:37] offset:3072
	global_load_dwordx4 v[136:139], v166, s[36:37] offset:3072
	ds_read_b128 v[64:67], v187 offset:49152
	v_exp_f32_e32 v242, v80
	s_waitcnt lgkmcnt(0)
	v_mfma_f32_32x32x16_bf16 v[64:79], v[64:67], v[96:99], 0
	ds_read_b128 v[82:85], v187 offset:57344
	v_exp_f32_e32 v245, v81
	s_waitcnt lgkmcnt(0)
	v_mfma_f32_32x32x16_bf16 v[80:95], v[82:85], v[96:99], 0
	ds_read_b128 v[238:241], v188 offset:49152
	v_exp_f32_e32 v248, v152
	s_waitcnt lgkmcnt(0)
	v_mfma_f32_32x32x16_bf16 v[64:79], v[238:241], v[100:103], v[64:79]
	ds_read_b128 v[238:241], v188 offset:57344
	v_exp_f32_e32 v251, v153
	s_waitcnt lgkmcnt(0)
	v_mfma_f32_32x32x16_bf16 v[80:95], v[238:241], v[100:103], v[80:95]
	ds_read_b128 v[238:241], v189 offset:49152
	v_add_f32_e32 v152, 0, v231
	v_add_f32_e32 v152, v235, v152
	v_add_f32_e32 v152, v230, v152
	v_exp_f32_e32 v252, v150
	s_waitcnt lgkmcnt(0)
	v_mfma_f32_32x32x16_bf16 v[64:79], v[238:241], v[104:107], v[64:79]
	ds_read_b128 v[238:241], v189 offset:57344
	v_add_f32_e32 v150, v232, v152
	v_add_f32_e32 v150, v233, v150
	v_add_f32_e32 v221, v236, v150
	v_exp_f32_e32 v253, v151
	s_waitcnt lgkmcnt(0)
	v_mfma_f32_32x32x16_bf16 v[80:95], v[238:241], v[104:107], v[80:95]
	ds_read_b128 v[150:153], v190 offset:49152
	v_add_f32_e32 v221, v234, v221
	v_add_f32_e32 v221, v237, v221
	v_add_f32_e32 v221, v156, v221
	v_exp_f32_e32 v209, v148
	s_waitcnt lgkmcnt(0)
	v_mfma_f32_32x32x16_bf16 v[64:79], v[150:153], v[108:111], v[64:79]
	ds_read_b128 v[150:153], v190 offset:57344
	v_add_f32_e32 v148, v157, v221
	v_add_f32_e32 v148, v158, v148
	v_add_f32_e32 v221, v159, v148
	v_exp_f32_e32 v210, v149
	s_waitcnt lgkmcnt(0)
	v_mfma_f32_32x32x16_bf16 v[80:95], v[150:153], v[108:111], v[80:95]
	ds_read_b128 v[148:151], v191 offset:49152
	v_add_f32_e32 v152, v228, v221
	v_add_f32_e32 v152, v229, v152
	v_add_f32_e32 v152, v154, v152
	v_exp_f32_e32 v211, v142
	s_waitcnt lgkmcnt(0)
	v_mfma_f32_32x32x16_bf16 v[64:79], v[148:151], v[112:115], v[64:79]
	ds_read_b128 v[148:151], v191 offset:57344
	v_add_f32_e32 v142, v155, v152
	v_add_f32_e32 v142, v242, v142
	v_add_f32_e32 v142, v245, v142
	v_exp_f32_e32 v212, v143
	s_waitcnt lgkmcnt(0)
	v_mfma_f32_32x32x16_bf16 v[80:95], v[148:151], v[112:115], v[80:95]
	ds_read_b128 v[148:151], v192 offset:49152
	v_add_f32_e32 v142, v248, v142
	v_add_f32_e32 v142, v251, v142
	v_add_f32_e32 v142, v252, v142
	v_exp_f32_e32 v214, v146
	s_waitcnt lgkmcnt(0)
	v_mfma_f32_32x32x16_bf16 v[64:79], v[148:151], v[116:119], v[64:79]
	ds_read_b128 v[148:151], v192 offset:57344
	v_add_f32_e32 v142, v253, v142
	v_add_f32_e32 v142, v209, v142
	v_add_f32_e32 v142, v210, v142
	v_exp_f32_e32 v215, v147
	s_waitcnt lgkmcnt(0)
	v_mfma_f32_32x32x16_bf16 v[80:95], v[148:151], v[116:119], v[80:95]
	ds_read_b128 v[146:149], v193 offset:49152
	v_add_f32_e32 v142, v211, v142
	v_add_f32_e32 v142, v212, v142
	v_add_f32_e32 v142, v214, v142
	v_exp_f32_e32 v216, v140
	s_waitcnt lgkmcnt(0)
	v_mfma_f32_32x32x16_bf16 v[64:79], v[146:149], v[120:123], v[64:79]
	ds_read_b128 v[146:149], v193 offset:57344
	v_add_f32_e32 v142, v215, v142
	v_cvt_pk_bf16_f32 v140, v231, v235
	v_add_f32_e32 v142, v216, v142
	v_exp_f32_e32 v217, v141
	s_waitcnt lgkmcnt(0)
	v_mfma_f32_32x32x16_bf16 v[80:95], v[146:149], v[120:123], v[80:95]
	ds_read_b128 v[146:149], v194 offset:49152
	v_add_f32_e32 v143, v217, v142
	v_cvt_pk_bf16_f32 v141, v230, v232
	v_cvt_pk_bf16_f32 v142, v233, v236
	v_exp_f32_e32 v218, v144
	s_waitcnt lgkmcnt(0)
	v_mfma_f32_32x32x16_bf16 v[64:79], v[146:149], v[124:127], v[64:79]
	ds_read_b128 v[146:149], v194 offset:57344
	v_add_f32_e32 v144, v218, v143
	v_cvt_pk_bf16_f32 v143, v234, v237
	v_permlane32_swap_b32_e32 v140, v142
	v_exp_f32_e32 v219, v145
	s_waitcnt lgkmcnt(0)
	v_mfma_f32_32x32x16_bf16 v[80:95], v[146:149], v[124:127], v[80:95]
	ds_read_b128 v[148:151], v195 offset:8192
	v_add_f32_e32 v204, v219, v144
	v_permlane32_swap_b32_e32 v141, v143
	v_mov_b32_e32 v221, v204
	ds_read_b128 v[230:233], v195 offset:12288
	v_cvt_pk_bf16_f32 v144, v156, v157
	v_cvt_pk_bf16_f32 v145, v158, v159
	ds_read_b128 v[156:159], v196
	v_cvt_pk_bf16_f32 v146, v228, v229
	ds_read_b128 v[234:237], v198
	s_waitcnt lgkmcnt(1)
	v_mfma_f32_32x32x16_bf16 v[80:95], v[230:233], v[156:159], v[80:95]
	ds_read_b128 v[228:231], v197 offset:12288
	s_waitcnt lgkmcnt(0)
	v_mfma_f32_32x32x16_bf16 v[80:95], v[228:231], v[234:237], v[80:95]
	ds_read_b128 v[228:231], v199 offset:12288
	ds_read_b128 v[238:241], v200
	s_waitcnt lgkmcnt(0)
	v_mfma_f32_32x32x16_bf16 v[80:95], v[228:231], v[238:241], v[80:95]
	v_permlane32_swap_b32_e32 v204, v221
	v_cvt_pk_bf16_f32 v147, v154, v155
	v_permlane32_swap_b32_e32 v144, v146
	ds_read_b128 v[228:231], v201 offset:12288
	v_mfma_f32_32x32x16_bf16 v[64:79], v[148:151], v[156:159], v[64:79]
	v_permlane32_swap_b32_e32 v145, v147
	ds_read_b128 v[148:151], v197 offset:8192
	v_cvt_pk_bf16_f32 v155, v218, v219
	ds_read_b128 v[156:159], v202
	s_waitcnt lgkmcnt(1)
	v_mfma_f32_32x32x16_bf16 v[64:79], v[148:151], v[234:237], v[64:79]
	ds_read_b128 v[148:151], v199 offset:8192
	v_cvt_pk_bf16_f32 v154, v216, v217
	s_waitcnt lgkmcnt(0)
	v_mfma_f32_32x32x16_bf16 v[64:79], v[148:151], v[238:241], v[64:79]
	ds_read_b128 v[150:153], v201 offset:8192
	s_waitcnt lgkmcnt(0)
; #define SBAR() __builtin_amdgcn_sched_barrier(0)
; #define SGB_QK() _Pragma("unroll") for (int g_ = 0; g_ < 24; ++g_) { __builtin_amdgcn_sched_group_barrier(0x008, 1, 0); __builtin_amdgcn_sched_group_barrier(0x100, 1, 0); \
;     __builtin_amdgcn_sched_group_barrier(0x002, 3, 0); __builtin_amdgcn_sched_group_barrier(0x400, 1, 0); }
; #define SLOAD(k0) do { SLOAD_KR(k0); SLOAD_V(k0); } while (0)
; #define SWRITE(b) do { SWRITE_KR(b); SWRITE_V(b); } while (0)
; DEVI void pv_d0(f32x16* o, const char* Vs, int r32, int hi, bf16x8 pa0, bf16x8 pa1, bf16x8 pa2, bf16x8 pa3) {
; #pragma unroll
;   for (int d0 = 0; d0 < 4; ++d0) {
;     const bf16x8 f0 = *reinterpret_cast<const bf16x8*>(Vs + RSWZ(d0 * 32 + r32, (0 * 16 + hi * 8) * 2));
;     const bf16x8 f1 = *reinterpret_cast<const bf16x8*>(Vs + RSWZ(d0 * 32 + r32, (1 * 16 + hi * 8) * 2));
;     const bf16x8 f2 = *reinterpret_cast<const bf16x8*>(Vs + RSWZ(d0 * 32 + r32, (2 * 16 + hi * 8) * 2));
;     const bf16x8 f3 = *reinterpret_cast<const bf16x8*>(Vs + RSWZ(d0 * 32 + r32, (3 * 16 + hi * 8) * 2));
;     o[d0] = __builtin_amdgcn_mfma_f32_32x32x16_bf16(pa0, f0, o[d0], 0, 0, 0);
;     o[d0] = __builtin_amdgcn_mfma_f32_32x32x16_bf16(pa1, f1, o[d0], 0, 0, 0);
;     o[d0] = __builtin_amdgcn_mfma_f32_32x32x16_bf16(pa2, f2, o[d0], 0, 0, 0);
;     o[d0] = __builtin_amdgcn_mfma_f32_32x32x16_bf16(pa3, f3, o[d0], 0, 0, 0);
;   }
; }
; DEVI void attn_item(const u16* __restrict__ Qb, const u16* __restrict__ KNh, const u16* __restrict__ VTh, int Lpad, const u16* __restrict__ KRb,
;                     const u16* __restrict__ SZb, u16* __restrict__ AOb, int NT, char* lds, const int wid_s_) {
;     ...
;   f32x16 pA0, pA1, pB0, pB1; float mnA, mnB, alA, alB; bf16x8 pa0, pa1, pa2, pa3;
;   SLOAD(0); SWAIT(); SWRITE(0); __syncthreads();
;   qkt(pA0, pA1, K_lds, R_lds, qr, Qrs, r32, hi); partialSM(pA0, pA1, m_reg, mnA, alA);
;   SLOAD(64);
;   SWAIT(); SWRITE(1); __syncthreads();
;   for (int j = 1; j + 1 < NT; j += 2) {
;     SLOAD_KR((j + 1) * 64);
;     SBAR(); qkt(pB0, pB1, K_lds + SHM_K, R_lds + SHM_R, qr, Qrs, r32, hi);
;     finishSM(pA0, pA1, alA, l_reg, pa0, pa1, pa2, pa3); SGB_QK(); SBAR();
;     SLOAD_V((j + 1) * 64); SBAR();
;     pv_d0(o, V_lds, r32, hi, pa0, pa1, pa2, pa3); partialSM(pB0, pB1, m_reg, mnB, alB);
;     SWRITE_KR(0);
;     __syncthreads(); SWAIT(); SWRITE_V(0);
;     RESC(alB); __syncthreads();
	v_mfma_f32_32x32x16_bf16 v[64:79], v[150:153], v[156:159], v[64:79]
	v_cvt_pk_bf16_f32 v153, v214, v215
	v_cvt_pk_bf16_f32 v152, v211, v212
	v_cvt_pk_bf16_f32 v151, v209, v210
	v_cvt_pk_bf16_f32 v149, v248, v251
	s_nop 1
	v_permlane32_swap_b32_e32 v149, v151
	v_cvt_pk_bf16_f32 v148, v242, v245
	v_mfma_f32_32x32x16_bf16 v[80:95], v[228:231], v[156:159], v[80:95]
	v_cvt_pk_bf16_f32 v150, v252, v253
	s_nop 1
	v_permlane32_swap_b32_e32 v148, v150
	v_permlane32_swap_b32_e32 v152, v154
	v_permlane32_swap_b32_e32 v153, v155
	global_load_dwordx4 v[228:231], v162, s[36:37] offset:3328
	global_load_dwordx4 v[232:235], v164, s[36:37] offset:3328
	ds_read_b128 v[236:239], v177
	ds_read_b128 v[240:243], v161
	ds_read_b128 v[244:247], v180
	ds_read_b128 v[248:251], v179
	s_waitcnt lgkmcnt(3)
	v_mfma_f32_32x32x16_bf16 v[16:31], v[140:143], v[236:239], v[16:31]
	ds_read_b128 v[236:239], v177 offset:4096
	s_waitcnt lgkmcnt(3)
	v_mfma_f32_32x32x16_bf16 v[16:31], v[144:147], v[240:243], v[16:31]
	ds_read_b128 v[240:243], v161 offset:4096
	s_waitcnt lgkmcnt(1)
	v_mfma_f32_32x32x16_bf16 v[48:63], v[140:143], v[236:239], v[48:63]
	ds_read_b128 v[236:239], v177 offset:8192
	v_mfma_f32_32x32x16_bf16 v[16:31], v[148:151], v[244:247], v[16:31]
	ds_read_b128 v[244:247], v180 offset:4096
	s_waitcnt lgkmcnt(2)
	v_mfma_f32_32x32x16_bf16 v[48:63], v[144:147], v[240:243], v[48:63]
	ds_read_b128 v[240:243], v161 offset:8192
	s_waitcnt lgkmcnt(2)
	v_mfma_f32_32x32x16_bf16 v[32:47], v[140:143], v[236:239], v[32:47]
	ds_read_b128 v[236:239], v177 offset:12288
	v_mfma_f32_32x32x16_bf16 v[16:31], v[152:155], v[248:251], v[16:31]
	ds_read_b128 v[248:251], v179 offset:4096
	s_waitcnt lgkmcnt(3)
	v_mfma_f32_32x32x16_bf16 v[48:63], v[148:151], v[244:247], v[48:63]
	ds_read_b128 v[244:247], v180 offset:8192
	s_waitcnt lgkmcnt(3)
	v_mfma_f32_32x32x16_bf16 v[32:47], v[144:147], v[240:243], v[32:47]
	ds_read_b128 v[240:243], v161 offset:12288
	s_waitcnt lgkmcnt(3)
	v_mfma_f32_32x32x16_bf16 v[0:15], v[140:143], v[236:239], v[0:15]
	v_max_f32_e32 v140, v65, v65
	v_max_f32_e32 v141, v64, v64
	v_max_f32_e32 v140, v141, v140
	v_max3_f32 v140, v140, v66, v67
	v_max3_f32 v140, v140, v68, v69
	v_max3_f32 v140, v140, v70, v71
	v_max3_f32 v140, v140, v72, v73
	v_max3_f32 v140, v140, v74, v75
	v_max3_f32 v140, v140, v76, v77
	s_waitcnt lgkmcnt(2)
	v_mfma_f32_32x32x16_bf16 v[48:63], v[152:155], v[248:251], v[48:63]
	ds_read_b128 v[248:251], v179 offset:8192
	v_max3_f32 v140, v140, v78, v79
	v_max3_f32 v140, v140, v80, v81
	v_max3_f32 v140, v140, v82, v83
	v_max3_f32 v140, v140, v84, v85
	v_max3_f32 v140, v140, v86, v87
	v_max3_f32 v140, v140, v88, v89
	s_waitcnt lgkmcnt(2)
	v_mfma_f32_32x32x16_bf16 v[32:47], v[148:151], v[244:247], v[32:47]
	ds_read_b128 v[244:247], v180 offset:12288
	v_max3_f32 v140, v140, v90, v91
	v_max3_f32 v140, v140, v92, v93
	v_max3_f32 v140, v140, v94, v95
	v_mov_b32_e32 v141, v140
	s_nop 1
	v_permlane32_swap_b32_e32 v140, v141
	s_waitcnt lgkmcnt(2)
	v_mfma_f32_32x32x16_bf16 v[0:15], v[144:147], v[240:243], v[0:15]
	v_max_f32_e32 v141, v141, v141
	v_max_f32_e32 v140, v140, v140
	v_max_f32_e32 v140, v140, v141
	v_sub_f32_e32 v141, v140, v222
	v_cmp_ge_f32_e32 vcc, s91, v141
	v_max_f32_e32 v141, v222, v222
	v_max_f32_e32 v140, v141, v140
	s_waitcnt lgkmcnt(1)
	v_mfma_f32_32x32x16_bf16 v[32:47], v[152:155], v[248:251], v[32:47]
	ds_read_b128 v[248:251], v179 offset:12288
	v_sub_f32_e32 v141, v222, v140
	v_mul_f32_e32 v141, 0x3dd53b94, v141
	v_exp_f32_e32 v141, v141
	s_cmp_eq_u64 vcc, exec
	s_cselect_b64 s[8:9], -1, 0
	s_waitcnt vmcnt(2)
	ds_write_b128 v184, v[128:131] offset:32768
	s_waitcnt lgkmcnt(2)
	v_mfma_f32_32x32x16_bf16 v[0:15], v[148:151], v[244:247], v[0:15]
	ds_write_b128 v184, v[132:135] offset:40960
	ds_write_b128 v186, v[136:139]
	s_waitcnt lgkmcnt(0)
	s_barrier
	s_waitcnt vmcnt(0)
	v_cndmask_b32_e64 v224, v141, 1.0, s[8:9]
	v_mfma_f32_32x32x16_bf16 v[0:15], v[152:155], v[248:251], v[0:15]
	v_cmp_gt_f32_e32 vcc, 1.0, v224
	ds_write_b128 v185, v[228:231]
	ds_write_b128 v185, v[232:235] offset:8192
	s_cbranch_vccz .LBB0_985
	s_and_saveexec_b64 s[14:15], s[6:7]
	ds_write_b32 v181, v224 offset:128
	s_or_b64 exec, exec, s[14:15]
	s_waitcnt lgkmcnt(0)
	v_add_u32_e32 v141, v178, v160
	ds_read_b128 v[128:131], v141 offset:224
	ds_read_b128 v[132:135], v141 offset:192
	ds_read_b128 v[136:139], v141 offset:160
	ds_read_b128 v[142:145], v141 offset:128
	s_waitcnt lgkmcnt(3)
	v_pk_mul_f32 v[28:29], v[28:29], v[128:129]
	s_waitcnt lgkmcnt(2)
	v_pk_mul_f32 v[24:25], v[24:25], v[132:133]
	s_waitcnt lgkmcnt(1)
	v_pk_mul_f32 v[20:21], v[20:21], v[136:137]
	v_pk_mul_f32 v[30:31], v[30:31], v[130:131]
	v_pk_mul_f32 v[26:27], v[26:27], v[134:135]
	v_pk_mul_f32 v[22:23], v[22:23], v[138:139]
	s_waitcnt lgkmcnt(0)
	v_pk_mul_f32 v[18:19], v[18:19], v[144:145]
	v_pk_mul_f32 v[16:17], v[16:17], v[142:143]
	v_pk_mul_f32 v[60:61], v[60:61], v[128:129]
	v_pk_mul_f32 v[56:57], v[56:57], v[132:133]
	v_pk_mul_f32 v[52:53], v[52:53], v[136:137]
	v_pk_mul_f32 v[62:63], v[62:63], v[130:131]
	v_pk_mul_f32 v[58:59], v[58:59], v[134:135]
	v_pk_mul_f32 v[54:55], v[54:55], v[138:139]
	v_pk_mul_f32 v[50:51], v[50:51], v[144:145]
	v_pk_mul_f32 v[48:49], v[48:49], v[142:143]
	v_pk_mul_f32 v[44:45], v[44:45], v[128:129]
	v_pk_mul_f32 v[40:41], v[40:41], v[132:133]
	v_pk_mul_f32 v[36:37], v[36:37], v[136:137]
	v_pk_mul_f32 v[46:47], v[46:47], v[130:131]
	v_pk_mul_f32 v[42:43], v[42:43], v[134:135]
	v_pk_mul_f32 v[38:39], v[38:39], v[138:139]
	v_pk_mul_f32 v[34:35], v[34:35], v[144:145]
	v_pk_mul_f32 v[32:33], v[32:33], v[142:143]
	v_pk_mul_f32 v[12:13], v[12:13], v[128:129]
	v_pk_mul_f32 v[8:9], v[8:9], v[132:133]
	v_pk_mul_f32 v[4:5], v[4:5], v[136:137]
	v_pk_mul_f32 v[14:15], v[14:15], v[130:131]
	v_pk_mul_f32 v[10:11], v[10:11], v[134:135]
	v_pk_mul_f32 v[6:7], v[6:7], v[138:139]
	v_pk_mul_f32 v[2:3], v[2:3], v[144:145]
	v_pk_mul_f32 v[0:1], v[0:1], v[142:143]
; #define SBAR() __builtin_amdgcn_sched_barrier(0)
; #define SGB_QK() _Pragma("unroll") for (int g_ = 0; g_ < 24; ++g_) { __builtin_amdgcn_sched_group_barrier(0x008, 1, 0); __builtin_amdgcn_sched_group_barrier(0x100, 1, 0); \
;     __builtin_amdgcn_sched_group_barrier(0x002, 3, 0); __builtin_amdgcn_sched_group_barrier(0x400, 1, 0); }
; #define SLOAD_KR(k0) do { const char* kb_ = (const char*)KNh + (size_t)(k0) * (LDK * 2); const char* kb2_ = kb_ + 32 * LDK * 2; const char* rb_ = (const char*)KRb + (size_t)(k0) * 128; \
;     ks0 = *reinterpret_cast<const bf16x8*>(kb_ + vo_k); ks1 = *reinterpret_cast<const bf16x8*>(kb2_ + vo_k);               \
;     rs0 = *reinterpret_cast<const bf16x8*>(rb_ + vo_r); } while (0)
; DEVI void partialSM(f32x16& p0, f32x16& p1, float& m_reg, float& mn, float& alpha) {
;     ...
;   else { mn = fmaxf(m_reg, pmax); alpha = __builtin_amdgcn_exp2f((m_reg - mn) * C); m_reg = mn; }
;   float mnC = -mn * C;
; #pragma unroll
;   for (int r = 0; r < 16; ++r) p0[r] = fmaf(p0[r], C, mnC);
; #pragma unroll
;   for (int r = 0; r < 16; ++r) p1[r] = fmaf(p1[r], C, mnC);
; #pragma unroll
;   for (int r = 0; r < 16; ++r) p0[r] = __builtin_amdgcn_exp2f(p0[r]);
; }
; DEVI void finishSM(f32x16& p0, f32x16& p1, float alpha, float& l_reg, bf16x8& pa0, bf16x8& pa1, bf16x8& pa2, bf16x8& pa3) {
; #pragma unroll
;   for (int r = 0; r < 16; ++r) p1[r] = __builtin_amdgcn_exp2f(p1[r]);
;   float ps = 0;
; #pragma unroll
;   for (int r = 0; r < 16; ++r) ps += p0[r];
; #pragma unroll
;   for (int r = 0; r < 16; ++r) ps += p1[r];
;   { auto rr = __builtin_amdgcn_permlane32_swap(__float_as_uint(ps), __float_as_uint(ps), false, false);
;     ps = __uint_as_float(rr[0]) + __uint_as_float(rr[1]); }
;   l_reg = l_reg * alpha + ps;
; DEVI void attn_item(const u16* __restrict__ Qb, const u16* __restrict__ KNh, const u16* __restrict__ VTh, int Lpad, const u16* __restrict__ KRb,
;                     const u16* __restrict__ SZb, u16* __restrict__ AOb, int NT, char* lds, const int wid_s_) {
;     ...
;     SLOAD_KR((j + 2) * 64);
;     SBAR(); qkt(pA0, pA1, K_lds, R_lds, qr, Qrs, r32, hi);
;     if (j + 1 == NT - 2) mask_tile(pA0, pA1, true);
;     finishSM(pB0, pB1, alB, l_reg, pa0, pa1, pa2, pa3); SGB_QK(); SBAR();
.LBB0_985:
	v_cndmask_b32_e64 v222, v140, v222, s[8:9]
	v_mul_f32_e32 v152, 0xbdd53b94, v222
	v_fmamk_f32 v66, v66, 0x3dd53b94, v152
	v_fmamk_f32 v67, v67, 0x3dd53b94, v152
	v_exp_f32_e32 v141, v66
	v_add_u32_e32 v66, 0x40000, v168
	v_fmamk_f32 v68, v68, 0x3dd53b94, v152
	v_exp_f32_e32 v236, v67
	v_fmamk_f32 v69, v69, 0x3dd53b94, v152
	v_exp_f32_e32 v237, v68
	v_add_u32_e32 v68, 0x60000, v168
	v_fmamk_f32 v128, v64, 0x3dd53b94, v152
	v_exp_f32_e32 v238, v69
	v_exp_f32_e32 v140, v128
	s_waitcnt lgkmcnt(0)
	s_barrier
	global_load_dwordx4 v[128:131], v66, s[36:37] offset:3072
	v_add_u32_e32 v66, 0x2000, v166
	global_load_dwordx4 v[132:135], v68, s[36:37] offset:3072
	global_load_dwordx4 v[136:139], v66, s[36:37] offset:3072
	v_fmamk_f32 v74, v74, 0x3dd53b94, v152
	v_fmamk_f32 v75, v75, 0x3dd53b94, v152
	v_exp_f32_e32 v228, v74
	v_exp_f32_e32 v229, v75
	v_fmamk_f32 v65, v65, 0x3dd53b94, v152
	v_fmamk_f32 v70, v70, 0x3dd53b94, v152
	v_fmamk_f32 v71, v71, 0x3dd53b94, v152
	v_fmamk_f32 v72, v72, 0x3dd53b94, v152
	v_fmamk_f32 v73, v73, 0x3dd53b94, v152
	v_fmamk_f32 v76, v76, 0x3dd53b94, v152
	v_fmamk_f32 v77, v77, 0x3dd53b94, v152
	v_fmamk_f32 v78, v78, 0x3dd53b94, v152
	v_fmamk_f32 v79, v79, 0x3dd53b94, v152
	v_fmamk_f32 v64, v80, 0x3dd53b94, v152
	v_fmamk_f32 v80, v81, 0x3dd53b94, v152
	v_fmamk_f32 v241, v82, 0x3dd53b94, v152
	v_fmamk_f32 v145, v83, 0x3dd53b94, v152
	v_fmamk_f32 v144, v84, 0x3dd53b94, v152
	v_fmamk_f32 v143, v85, 0x3dd53b94, v152
	v_fmamk_f32 v142, v86, 0x3dd53b94, v152
	v_fmamk_f32 v239, v87, 0x3dd53b94, v152
	v_fmamk_f32 v154, v88, 0x3dd53b94, v152
	v_fmamk_f32 v150, v89, 0x3dd53b94, v152
	v_fmamk_f32 v146, v90, 0x3dd53b94, v152
	v_fmamk_f32 v147, v91, 0x3dd53b94, v152
	v_fmamk_f32 v148, v92, 0x3dd53b94, v152
	v_exp_f32_e32 v240, v65
	v_exp_f32_e32 v234, v70
	v_exp_f32_e32 v235, v71
	v_exp_f32_e32 v232, v72
	v_exp_f32_e32 v233, v73
	v_exp_f32_e32 v230, v76
	v_exp_f32_e32 v231, v77
	v_exp_f32_e32 v153, v78
	v_exp_f32_e32 v155, v79
	v_fmamk_f32 v149, v93, 0x3dd53b94, v152
	v_fmamk_f32 v151, v94, 0x3dd53b94, v152
	v_fmac_f32_e32 v152, 0x3dd53b94, v95
	ds_read_b128 v[66:69], v187 offset:32768
	v_add_f32_e32 v65, 0, v140
	v_add_f32_e32 v65, v240, v65
	v_add_f32_e32 v81, v141, v65
	v_exp_f32_e32 v209, v64
	s_cmp_eq_u32 s4, s2
	s_cselect_b64 vcc, -1, 0
	s_waitcnt lgkmcnt(0)
	v_mfma_f32_32x32x16_bf16 v[64:79], v[66:69], v[96:99], 0
	ds_read_b128 v[82:85], v187 offset:40960
	v_add_f32_e32 v81, v236, v81
	v_add_f32_e32 v81, v237, v81
	v_add_f32_e32 v210, v238, v81
	v_exp_f32_e32 v211, v80
	s_waitcnt lgkmcnt(0)
	v_mfma_f32_32x32x16_bf16 v[80:95], v[82:85], v[96:99], 0
	ds_read_b128 v[170:173], v188 offset:32768
	v_add_f32_e32 v210, v234, v210
	v_add_f32_e32 v210, v235, v210
	v_add_f32_e32 v210, v232, v210
	v_exp_f32_e32 v212, v241
	s_waitcnt lgkmcnt(0)
	v_mfma_f32_32x32x16_bf16 v[64:79], v[170:173], v[100:103], v[64:79]
	ds_read_b128 v[170:173], v188 offset:40960
	v_add_f32_e32 v210, v233, v210
	v_add_f32_e32 v210, v228, v210
	v_add_f32_e32 v210, v229, v210
	v_exp_f32_e32 v214, v145
	s_waitcnt lgkmcnt(0)
	v_mfma_f32_32x32x16_bf16 v[80:95], v[170:173], v[100:103], v[80:95]
	ds_read_b128 v[170:173], v189 offset:32768
	v_add_f32_e32 v145, v230, v210
	v_add_f32_e32 v145, v231, v145
	v_add_f32_e32 v145, v153, v145
	v_exp_f32_e32 v210, v144
	s_waitcnt lgkmcnt(0)
	v_mfma_f32_32x32x16_bf16 v[64:79], v[170:173], v[104:107], v[64:79]
	ds_read_b128 v[170:173], v189 offset:40960
	v_add_f32_e32 v144, v155, v145
	v_add_f32_e32 v144, v209, v144
	v_add_f32_e32 v144, v211, v144
	v_exp_f32_e32 v215, v143
	s_waitcnt lgkmcnt(0)
	v_mfma_f32_32x32x16_bf16 v[80:95], v[170:173], v[104:107], v[80:95]
	ds_read_b128 v[170:173], v190 offset:32768
	v_add_f32_e32 v143, v212, v144
	v_add_f32_e32 v143, v214, v143
	v_add_f32_e32 v216, v210, v143
	v_exp_f32_e32 v217, v142
	s_waitcnt lgkmcnt(0)
	v_mfma_f32_32x32x16_bf16 v[64:79], v[170:173], v[108:111], v[64:79]
	ds_read_b128 v[142:145], v190 offset:40960
	v_add_f32_e32 v170, v215, v216
	v_cvt_pk_bf16_f32 v140, v140, v240
	v_add_f32_e32 v216, v217, v170
	v_exp_f32_e32 v218, v239
	s_waitcnt lgkmcnt(0)
	v_mfma_f32_32x32x16_bf16 v[80:95], v[142:145], v[108:111], v[80:95]
	ds_read_b128 v[170:173], v191 offset:32768
	v_cvt_pk_bf16_f32 v141, v141, v236
	v_cvt_pk_bf16_f32 v142, v237, v238
	v_add_f32_e32 v143, v218, v216
	v_exp_f32_e32 v154, v154
	s_waitcnt lgkmcnt(0)
	v_mfma_f32_32x32x16_bf16 v[64:79], v[170:173], v[112:115], v[64:79]
	ds_read_b128 v[170:173], v191 offset:40960
	v_add_f32_e32 v144, v154, v143
	v_cvt_pk_bf16_f32 v143, v234, v235
	v_permlane32_swap_b32_e32 v140, v142
	v_exp_f32_e32 v216, v150
	s_waitcnt lgkmcnt(0)
	v_mfma_f32_32x32x16_bf16 v[80:95], v[170:173], v[112:115], v[80:95]
	ds_read_b128 v[170:173], v192 offset:32768
	v_add_f32_e32 v145, v216, v144
	v_permlane32_swap_b32_e32 v141, v143
	v_cvt_pk_bf16_f32 v144, v232, v233
	v_exp_f32_e32 v219, v146
	s_waitcnt lgkmcnt(0)
	v_mfma_f32_32x32x16_bf16 v[64:79], v[170:173], v[116:119], v[64:79]
	ds_read_b128 v[170:173], v192 offset:40960
	v_add_f32_e32 v150, v219, v145
	v_cvt_pk_bf16_f32 v145, v228, v229
	v_cvt_pk_bf16_f32 v146, v230, v231
	v_exp_f32_e32 v236, v147
	s_waitcnt lgkmcnt(0)
	v_mfma_f32_32x32x16_bf16 v[80:95], v[170:173], v[116:119], v[80:95]
	ds_read_b128 v[170:173], v193 offset:32768
	v_add_f32_e32 v150, v236, v150
	v_cvt_pk_bf16_f32 v147, v153, v155
	v_permlane32_swap_b32_e32 v144, v146
	v_exp_f32_e32 v155, v148
	s_waitcnt lgkmcnt(0)
	v_mfma_f32_32x32x16_bf16 v[64:79], v[170:173], v[120:123], v[64:79]
	ds_read_b128 v[170:173], v193 offset:40960
	v_add_f32_e32 v150, v155, v150
	v_permlane32_swap_b32_e32 v145, v147
	v_cvt_pk_bf16_f32 v148, v209, v211
	v_exp_f32_e32 v209, v149
	s_waitcnt lgkmcnt(0)
; DEVI void mask_tile(f32x16& p0, f32x16& p1, bool nv16) {
; #pragma unroll
;   for (int r = 0; r < 16; ++r) { if (!(nv16 && r < 8)) p0[r] = -1e30f; p1[r] = -1e30f; }
; }
; DEVI void qkt(f32x16& p0, f32x16& p1, const char* Ks, const char* Rs, const bf16x8* qr, const char* Qrs, int r32, int hi) {
;   p0 = f32x16{}; p1 = f32x16{};
; #pragma unroll
;   for (int d0 = 0; d0 < 8; ++d0) { int cb = (d0 * 16 + hi * 8) * 2;
;     bf16x8 b0 = *reinterpret_cast<const bf16x8*>(Ks + KSWZ(r32, cb));
;     bf16x8 b1 = *reinterpret_cast<const bf16x8*>(Ks + KSWZ(32 + r32, cb));
;     p0 = __builtin_amdgcn_mfma_f32_32x32x16_bf16(b0, qr[d0], p0, 0, 0, 0);
;     p1 = __builtin_amdgcn_mfma_f32_32x32x16_bf16(b1, qr[d0], p1, 0, 0, 0); }
; #pragma unroll
;   for (int d0 = 0; d0 < 4; ++d0) { int cb = (d0 * 16 + hi * 8) * 2;
;     bf16x8 b0 = *reinterpret_cast<const bf16x8*>(Rs + RSWZ(r32, cb));
;     bf16x8 b1 = *reinterpret_cast<const bf16x8*>(Rs + RSWZ(32 + r32, cb));
;     bf16x8 qf = *reinterpret_cast<const bf16x8*>(Qrs + RSWZ(r32, cb));
;     p0 = __builtin_amdgcn_mfma_f32_32x32x16_bf16(b0, qf, p0, 0, 0, 0);
;     p1 = __builtin_amdgcn_mfma_f32_32x32x16_bf16(b1, qf, p1, 0, 0, 0); }
; }
; DEVI void pv_d0(f32x16* o, const char* Vs, int r32, int hi, bf16x8 pa0, bf16x8 pa1, bf16x8 pa2, bf16x8 pa3) {
; #pragma unroll
;   for (int d0 = 0; d0 < 4; ++d0) {
;     const bf16x8 f0 = *reinterpret_cast<const bf16x8*>(Vs + RSWZ(d0 * 32 + r32, (0 * 16 + hi * 8) * 2));
;     const bf16x8 f1 = *reinterpret_cast<const bf16x8*>(Vs + RSWZ(d0 * 32 + r32, (1 * 16 + hi * 8) * 2));
;     const bf16x8 f2 = *reinterpret_cast<const bf16x8*>(Vs + RSWZ(d0 * 32 + r32, (2 * 16 + hi * 8) * 2));
;     const bf16x8 f3 = *reinterpret_cast<const bf16x8*>(Vs + RSWZ(d0 * 32 + r32, (3 * 16 + hi * 8) * 2));
;     o[d0] = __builtin_amdgcn_mfma_f32_32x32x16_bf16(pa0, f0, o[d0], 0, 0, 0);
;     o[d0] = __builtin_amdgcn_mfma_f32_32x32x16_bf16(pa1, f1, o[d0], 0, 0, 0);
;     o[d0] = __builtin_amdgcn_mfma_f32_32x32x16_bf16(pa2, f2, o[d0], 0, 0, 0);
;     o[d0] = __builtin_amdgcn_mfma_f32_32x32x16_bf16(pa3, f3, o[d0], 0, 0, 0);
;   }
; }
	v_mfma_f32_32x32x16_bf16 v[80:95], v[170:173], v[120:123], v[80:95]
	ds_read_b128 v[170:173], v194 offset:32768
	v_add_f32_e32 v153, v209, v150
	v_cvt_pk_bf16_f32 v149, v212, v214
	v_cvt_pk_bf16_f32 v150, v210, v215
	v_exp_f32_e32 v210, v151
	s_waitcnt lgkmcnt(0)
	v_mfma_f32_32x32x16_bf16 v[64:79], v[170:173], v[124:127], v[64:79]
	ds_read_b128 v[170:173], v194 offset:40960
	v_add_f32_e32 v153, v210, v153
	v_cvt_pk_bf16_f32 v151, v217, v218
	v_permlane32_swap_b32_e32 v148, v150
	v_exp_f32_e32 v211, v152
	s_waitcnt lgkmcnt(0)
	v_mfma_f32_32x32x16_bf16 v[80:95], v[170:173], v[124:127], v[80:95]
	ds_read_b128 v[228:231], v195
	v_add_f32_e32 v170, v211, v153
	v_mov_b32_e32 v171, v170
	v_permlane32_swap_b32_e32 v149, v151
	ds_read_b128 v[232:235], v195 offset:4096
	v_permlane32_swap_b32_e32 v170, v171
	v_cvt_pk_bf16_f32 v152, v154, v216
	v_cvt_pk_bf16_f32 v153, v219, v236
	ds_read_b128 v[236:239], v196
	s_waitcnt lgkmcnt(0)
	v_mfma_f32_32x32x16_bf16 v[64:79], v[228:231], v[236:239], v[64:79]
	ds_read_b128 v[228:231], v197
	v_mfma_f32_32x32x16_bf16 v[80:95], v[232:235], v[236:239], v[80:95]
	ds_read_b128 v[240:243], v198
	ds_read_b128 v[232:235], v202
	ds_read_b128 v[236:239], v199 offset:4096
	s_waitcnt lgkmcnt(2)
	v_mfma_f32_32x32x16_bf16 v[64:79], v[228:231], v[240:243], v[64:79]
	ds_read_b128 v[228:231], v199
	ds_read_b128 v[244:247], v200
	s_waitcnt lgkmcnt(0)
	v_mfma_f32_32x32x16_bf16 v[64:79], v[228:231], v[244:247], v[64:79]
	ds_read_b128 v[228:231], v201
	s_waitcnt lgkmcnt(0)
	v_mfma_f32_32x32x16_bf16 v[64:79], v[228:231], v[232:235], v[64:79]
	ds_read_b128 v[226:229], v197 offset:4096
	s_waitcnt lgkmcnt(0)
	v_mfma_f32_32x32x16_bf16 v[80:95], v[226:229], v[240:243], v[80:95]
	ds_read_b128 v[240:243], v201 offset:4096
	v_cvt_pk_bf16_f32 v154, v155, v209
	v_cvt_pk_bf16_f32 v155, v210, v211
	s_nop 0
	v_permlane32_swap_b32_e32 v152, v154
	v_permlane32_swap_b32_e32 v153, v155
	v_mfma_f32_32x32x16_bf16 v[80:95], v[236:239], v[244:247], v[80:95]
	s_nop 1
	v_cndmask_b32_e32 v229, v72, v208, vcc
	v_cndmask_b32_e32 v227, v76, v208, vcc
	v_cndmask_b32_e32 v228, v73, v208, vcc
	s_waitcnt lgkmcnt(0)
	v_mfma_f32_32x32x16_bf16 v[80:95], v[240:243], v[232:235], v[80:95]
	s_nop 11
	v_cndmask_b32_e32 v73, v95, v208, vcc
	v_cndmask_b32_e32 v226, v74, v208, vcc
	v_cndmask_b32_e32 v172, v79, v208, vcc
	v_cndmask_b32_e32 v173, v78, v208, vcc
	v_cndmask_b32_e32 v223, v77, v208, vcc
	v_cndmask_b32_e32 v225, v75, v208, vcc
	v_cndmask_b32_e32 v72, v94, v208, vcc
	v_cndmask_b32_e32 v75, v93, v208, vcc
	v_cndmask_b32_e32 v74, v92, v208, vcc
	v_cndmask_b32_e32 v77, v91, v208, vcc
	v_cndmask_b32_e32 v76, v90, v208, vcc
	v_cndmask_b32_e32 v79, v89, v208, vcc
	v_cndmask_b32_e32 v78, v88, v208, vcc
	v_cndmask_b32_e32 v87, v87, v208, vcc
	v_cndmask_b32_e32 v86, v86, v208, vcc
	v_cndmask_b32_e32 v85, v85, v208, vcc
	v_cndmask_b32_e32 v84, v84, v208, vcc
	v_cndmask_b32_e32 v83, v83, v208, vcc
	v_cndmask_b32_e32 v82, v82, v208, vcc
	v_cndmask_b32_e32 v81, v81, v208, vcc
	v_cndmask_b32_e32 v80, v80, v208, vcc
	global_load_dwordx4 v[90:93], v162, s[36:37] offset:3456
	global_load_dwordx4 v[156:159], v164, s[36:37] offset:3456
	ds_read_b128 v[230:233], v177 offset:16384
	ds_read_b128 v[234:237], v161 offset:16384
	ds_read_b128 v[238:241], v180 offset:16384
	v_max_f32_e32 v88, v65, v65
	v_max_f32_e32 v89, v64, v64
	s_waitcnt lgkmcnt(2)
	v_mfma_f32_32x32x16_bf16 v[16:31], v[140:143], v[230:233], v[16:31]
	ds_read_b128 v[230:233], v177 offset:20480
	v_max_f32_e32 v88, v89, v88
	v_max3_f32 v88, v88, v66, v67
	v_max3_f32 v88, v88, v68, v69
	ds_read_b128 v[242:245], v179 offset:16384
	v_max3_f32 v88, v88, v70, v71
	v_max3_f32 v88, v88, v229, v228
	s_waitcnt lgkmcnt(1)
	v_mfma_f32_32x32x16_bf16 v[48:63], v[140:143], v[230:233], v[48:63]
	ds_read_b128 v[230:233], v177 offset:24576
	v_max3_f32 v88, v88, v226, v225
	v_max3_f32 v88, v88, v227, v223
	v_max3_f32 v88, v88, v173, v172
	v_max3_f32 v88, v88, v80, v81
	v_max3_f32 v88, v88, v82, v83
	v_max3_f32 v88, v88, v84, v85
	v_mfma_f32_32x32x16_bf16 v[16:31], v[144:147], v[234:237], v[16:31]
	ds_read_b128 v[234:237], v161 offset:20480
	v_max3_f32 v88, v88, v86, v87
	v_max3_f32 v88, v88, v78, v79
	v_max3_f32 v88, v88, v76, v77
	v_max3_f32 v88, v88, v74, v75
	v_max3_f32 v88, v88, v72, v73
	v_mov_b32_e32 v89, v88
	s_waitcnt lgkmcnt(1)
	v_mfma_f32_32x32x16_bf16 v[32:47], v[140:143], v[230:233], v[32:47]
	ds_read_b128 v[230:233], v177 offset:28672
	v_permlane32_swap_b32_e32 v88, v89
	v_max_f32_e32 v89, v89, v89
	v_max_f32_e32 v88, v88, v88
	v_max_f32_e32 v88, v88, v89
	v_sub_f32_e32 v89, v88, v222
	s_waitcnt lgkmcnt(1)
	v_mfma_f32_32x32x16_bf16 v[48:63], v[144:147], v[234:237], v[48:63]
	ds_read_b128 v[234:237], v161 offset:24576
	v_cmp_ge_f32_e32 vcc, s91, v89
	v_max_f32_e32 v89, v222, v222
	v_max_f32_e32 v89, v89, v88
	v_sub_f32_e32 v88, v222, v89
	v_mul_f32_e32 v88, 0x3dd53b94, v88
	v_exp_f32_e32 v88, v88
	s_waitcnt lgkmcnt(1)
	v_mfma_f32_32x32x16_bf16 v[0:15], v[140:143], v[230:233], v[0:15]
	s_cmp_eq_u64 vcc, exec
	s_cselect_b64 s[8:9], -1, 0
	v_cndmask_b32_e64 v88, v88, 1.0, s[8:9]
	v_cmp_gt_f32_e32 vcc, 1.0, v88
	v_mfma_f32_32x32x16_bf16 v[16:31], v[148:151], v[238:241], v[16:31]
	ds_read_b128 v[238:241], v180 offset:20480
	s_waitcnt lgkmcnt(1)
	v_mfma_f32_32x32x16_bf16 v[32:47], v[144:147], v[234:237], v[32:47]
	ds_read_b128 v[234:237], v161 offset:28672
	s_waitcnt lgkmcnt(1)
	v_mfma_f32_32x32x16_bf16 v[48:63], v[148:151], v[238:241], v[48:63]
	ds_read_b128 v[238:241], v180 offset:24576
	s_waitcnt lgkmcnt(1)
	v_mfma_f32_32x32x16_bf16 v[0:15], v[144:147], v[234:237], v[0:15]
	v_mfma_f32_32x32x16_bf16 v[16:31], v[152:155], v[242:245], v[16:31]
	ds_read_b128 v[242:245], v179 offset:20480
	s_waitcnt lgkmcnt(1)
	v_mfma_f32_32x32x16_bf16 v[32:47], v[148:151], v[238:241], v[32:47]
	ds_read_b128 v[238:241], v180 offset:28672
	s_waitcnt lgkmcnt(1)
	v_mfma_f32_32x32x16_bf16 v[48:63], v[152:155], v[242:245], v[48:63]
	ds_read_b128 v[242:245], v179 offset:24576
	s_waitcnt lgkmcnt(1)
	v_mfma_f32_32x32x16_bf16 v[0:15], v[148:151], v[238:241], v[0:15]
	s_waitcnt lgkmcnt(0)
	v_mfma_f32_32x32x16_bf16 v[32:47], v[152:155], v[242:245], v[32:47]
	ds_read_b128 v[242:245], v179 offset:28672
	s_waitcnt vmcnt(2)
	ds_write_b128 v184, v[128:131] offset:49152
	ds_write_b128 v184, v[132:135] offset:57344
	ds_write_b128 v203, v[136:139]
	s_waitcnt lgkmcnt(0)
	s_barrier
; #define SWRITE_V(b) do { *(bf16x8*)(V_lds + (b) * SHM_V + RSWZ(vd, vc * 16)) = vs0; *(bf16x8*)(V_lds + (b) * SHM_V + RSWZ(vd + 64, vc * 16)) = vs1; } while (0)
; #define SWAIT() asm volatile("s_waitcnt vmcnt(0)" ::: "memory")
; #define RESC(a) do { if (__any((a) < 1.f)) { if (hi == 0) al_l[r32] = (a); asm volatile("s_waitcnt lgkmcnt(0)" ::: "memory"); \
;     _Pragma("unroll") for (int d = 0; d < 4; ++d) _Pragma("unroll") for (int r = 0; r < 16; ++r) o[d][r] *= al_l[crow(r, hi)]; } } while (0)
; DEVI void attn_item(const u16* __restrict__ Qb, const u16* __restrict__ KNh, const u16* __restrict__ VTh, int Lpad, const u16* __restrict__ KRb,
;                     const u16* __restrict__ SZb, u16* __restrict__ AOb, int NT, char* lds, const int wid_s_) {
;     ...
;     __syncthreads(); SWAIT(); SWRITE_V(1);
;     RESC(alA); __syncthreads();
	v_mfma_f32_32x32x16_bf16 v[0:15], v[152:155], v[242:245], v[0:15]
	s_waitcnt vmcnt(0)
	ds_write_b128 v185, v[90:93] offset:16384
	ds_write_b128 v185, v[156:159] offset:24576
	s_cbranch_vccz .LBB0_989
	s_and_saveexec_b64 s[14:15], s[6:7]
	ds_write_b32 v181, v88 offset:128
	s_or_b64 exec, exec, s[14:15]
	s_waitcnt lgkmcnt(0)
	v_add_u32_e32 v94, v178, v160
	ds_read_b128 v[90:93], v94 offset:224
	ds_read_b128 v[128:131], v94 offset:192
	ds_read_b128 v[132:135], v94 offset:160
	ds_read_b128 v[136:139], v94 offset:128
	s_waitcnt lgkmcnt(3)
	v_pk_mul_f32 v[28:29], v[28:29], v[90:91]
	s_waitcnt lgkmcnt(2)
	v_pk_mul_f32 v[24:25], v[24:25], v[128:129]
	s_waitcnt lgkmcnt(1)
	v_pk_mul_f32 v[20:21], v[20:21], v[132:133]
	v_pk_mul_f32 v[30:31], v[30:31], v[92:93]
	v_pk_mul_f32 v[26:27], v[26:27], v[130:131]
	v_pk_mul_f32 v[22:23], v[22:23], v[134:135]
	s_waitcnt lgkmcnt(0)
	v_pk_mul_f32 v[18:19], v[18:19], v[138:139]
	v_pk_mul_f32 v[16:17], v[16:17], v[136:137]
	v_pk_mul_f32 v[60:61], v[60:61], v[90:91]
	v_pk_mul_f32 v[56:57], v[56:57], v[128:129]
	v_pk_mul_f32 v[52:53], v[52:53], v[132:133]
	v_pk_mul_f32 v[62:63], v[62:63], v[92:93]
	v_pk_mul_f32 v[58:59], v[58:59], v[130:131]
	v_pk_mul_f32 v[54:55], v[54:55], v[134:135]
	v_pk_mul_f32 v[50:51], v[50:51], v[138:139]
	v_pk_mul_f32 v[48:49], v[48:49], v[136:137]
	v_pk_mul_f32 v[44:45], v[44:45], v[90:91]
	v_pk_mul_f32 v[40:41], v[40:41], v[128:129]
	v_pk_mul_f32 v[36:37], v[36:37], v[132:133]
	v_pk_mul_f32 v[46:47], v[46:47], v[92:93]
	v_pk_mul_f32 v[42:43], v[42:43], v[130:131]
	v_pk_mul_f32 v[38:39], v[38:39], v[134:135]
	v_pk_mul_f32 v[34:35], v[34:35], v[138:139]
	v_pk_mul_f32 v[32:33], v[32:33], v[136:137]
	v_pk_mul_f32 v[12:13], v[12:13], v[90:91]
	v_pk_mul_f32 v[8:9], v[8:9], v[128:129]
	v_pk_mul_f32 v[4:5], v[4:5], v[132:133]
	v_pk_mul_f32 v[14:15], v[14:15], v[92:93]
	v_pk_mul_f32 v[10:11], v[10:11], v[130:131]
	v_pk_mul_f32 v[6:7], v[6:7], v[134:135]
	v_pk_mul_f32 v[2:3], v[2:3], v[138:139]
	v_pk_mul_f32 v[0:1], v[0:1], v[136:137]
